# accumulator zeroing before each GEMM unit done with 64 v_mov_b64 instead of 127 v_mov_b32 (9 blocks)
# baseline (speedup 1.0000x reference)
.LBB0_206:
	s_ashr_i32 s27, s26, 31
	s_lshl_b64 s[30:31], s[26:27], 18
	s_add_u32 s30, s41, s30
	s_addc_u32 s31, s42, s31
	s_and_b64 s[0:1], s[0:1], exec
	s_cselect_b32 s25, s31, s39
	s_cselect_b32 s27, s30, s38
	s_add_u32 s0, s38, 0x20080
	s_addc_u32 s1, s39, 0
	s_add_u32 s60, s36, 0x100
	v_mov_b32_e32 v2, 0
	s_addc_u32 s61, s37, 0
	s_mov_b32 s62, -2
	v_mov_b64_e32 v[2:3], 0
	v_mov_b64_e32 v[4:5], 0
	v_mov_b64_e32 v[6:7], 0
	v_mov_b64_e32 v[8:9], 0
	v_mov_b64_e32 v[10:11], 0
	v_mov_b64_e32 v[12:13], 0
	v_mov_b64_e32 v[14:15], 0
	v_mov_b64_e32 v[16:17], 0
	v_mov_b64_e32 v[18:19], 0
	v_mov_b64_e32 v[20:21], 0
	v_mov_b64_e32 v[22:23], 0
	v_mov_b64_e32 v[24:25], 0
	v_mov_b64_e32 v[26:27], 0
	v_mov_b64_e32 v[28:29], 0
	v_mov_b64_e32 v[30:31], 0
	v_mov_b64_e32 v[32:33], 0
	v_mov_b64_e32 v[34:35], 0
	v_mov_b64_e32 v[36:37], 0
	v_mov_b64_e32 v[38:39], 0
	v_mov_b64_e32 v[40:41], 0
	v_mov_b64_e32 v[42:43], 0
	v_mov_b64_e32 v[44:45], 0
	v_mov_b64_e32 v[46:47], 0
	v_mov_b64_e32 v[48:49], 0
	v_mov_b64_e32 v[50:51], 0
	v_mov_b64_e32 v[52:53], 0
	v_mov_b64_e32 v[54:55], 0
	v_mov_b64_e32 v[56:57], 0
	v_mov_b64_e32 v[58:59], 0
	v_mov_b64_e32 v[60:61], 0
	v_mov_b64_e32 v[62:63], 0
	v_mov_b64_e32 v[64:65], 0
	v_mov_b64_e32 v[66:67], 0
	v_mov_b64_e32 v[68:69], 0
	v_mov_b64_e32 v[70:71], 0
	v_mov_b64_e32 v[72:73], 0
	v_mov_b64_e32 v[74:75], 0
	v_mov_b64_e32 v[76:77], 0
	v_mov_b64_e32 v[78:79], 0
	v_mov_b64_e32 v[80:81], 0
	v_mov_b64_e32 v[82:83], 0
	v_mov_b64_e32 v[84:85], 0
	v_mov_b64_e32 v[86:87], 0
	v_mov_b64_e32 v[88:89], 0
	v_mov_b64_e32 v[90:91], 0
	v_mov_b64_e32 v[92:93], 0
	v_mov_b64_e32 v[94:95], 0
	v_mov_b64_e32 v[96:97], 0
	v_mov_b64_e32 v[98:99], 0
	v_mov_b64_e32 v[100:101], 0
	v_mov_b64_e32 v[102:103], 0
	v_mov_b64_e32 v[104:105], 0
	v_mov_b64_e32 v[106:107], 0
	v_mov_b64_e32 v[108:109], 0
	v_mov_b64_e32 v[110:111], 0
	v_mov_b64_e32 v[112:113], 0
	v_mov_b64_e32 v[114:115], 0
	v_mov_b64_e32 v[116:117], 0
	v_mov_b64_e32 v[118:119], 0
	v_mov_b64_e32 v[120:121], 0
	v_mov_b64_e32 v[122:123], 0
	v_mov_b64_e32 v[124:125], 0
	v_mov_b64_e32 v[126:127], 0
	v_mov_b64_e32 v[128:129], 0
	s_nop 0

.LBB0_275:
	v_lshrrev_b32_e32 v18, 1, v5
	v_and_b32_e32 v18, 24, v18
	v_and_b32_e32 v9, 15, v5
	v_lshlrev_b32_e32 v19, 1, v18
	v_lshlrev_b32_e32 v5, 2, v5
	v_mov_b32_e32 v133, v155
	v_lshl_or_b32 v168, s9, 6, v9
	v_lshl_or_b32 v9, v9, 6, v19
	s_lshl_b32 s9, s9, 13
	v_and_b32_e32 v5, 32, v5
	v_lshl_add_u64 v[10:11], s[10:11], 0, v[132:133]
	v_mov_b32_e32 v137, v155
	v_bitop3_b32 v19, v9, s9, v5 bitop3:0xde
	s_lshl_b32 s9, s12, 5
	v_lshl_add_u64 v[12:13], s[10:11], 0, v[136:137]
	v_mov_b32_e32 v131, v155
	s_and_b32 s9, s9, 0x60
	s_add_i32 m0, s81, 0x18000
	v_lshl_add_u64 v[10:11], v[10:11], 0, s[34:35]
	v_lshl_add_u64 v[14:15], s[60:61], 0, v[130:131]
	v_mov_b32_e32 v135, v155
	s_lshl_b32 s12, s9, 7
	s_waitcnt vmcnt(2)
	s_barrier
	global_load_lds_dwordx4 v[10:11], off
	v_lshl_add_u64 v[10:11], v[12:13], 0, s[34:35]
	s_add_i32 m0, s81, 0x1a000
	s_add_i32 s85, s81, 0x8000
	s_add_i32 s86, s81, 0xa000
	v_lshl_add_u64 v[16:17], s[60:61], 0, v[134:135]
	v_bitop3_b32 v169, v9, s12, v5 bitop3:0xde
	global_load_lds_dwordx4 v[10:11], off
	v_lshl_add_u64 v[10:11], v[14:15], 0, s[34:35]
	s_mov_b32 m0, s85
	s_add_u32 s12, s10, 0x80080
	global_load_lds_dwordx4 v[10:11], off
	v_lshl_add_u64 v[10:11], v[16:17], 0, s[34:35]
	s_mov_b32 m0, s86
	s_addc_u32 s13, s11, 0
	global_load_lds_dwordx4 v[10:11], off
	s_add_i32 m0, s81, 0x1c000
	v_lshl_add_u64 v[10:11], s[12:13], 0, v[132:133]
	global_load_lds_dwordx4 v[10:11], off
	v_lshl_add_u64 v[10:11], s[12:13], 0, v[136:137]
	s_add_i32 m0, s81, 0x1e000
	v_lshlrev_b32_e32 v5, 15, v2
	global_load_lds_dwordx4 v[10:11], off
	v_and_b32_e32 v5, 0xffff0000, v5
	v_lshl_add_u32 v3, v3, 12, v5
	v_and_b32_e32 v2, 1, v2
	v_lshl_or_b32 v2, v2, 6, v3
	v_lshl_add_u32 v138, v4, 1, v2
	v_lshlrev_b32_e32 v2, 15, v6
	v_and_b32_e32 v2, 0xffff0000, v2
	s_cmpk_lt_u32 s8, 0x100
	v_or_b32_e32 v170, s9, v18
	v_lshl_add_u32 v2, v7, 12, v2
	v_and_b32_e32 v3, 1, v6
	v_readlane_b32 s8, v241, 26
	s_waitcnt vmcnt(6)
	v_lshl_or_b32 v2, v3, 6, v2
	v_readlane_b32 s9, v241, 27
	v_lshl_add_u32 v140, v8, 1, v2
	v_mov_b32_e32 v2, 0
	s_mov_b32 s87, s8
	v_readlane_b32 s8, v241, 20
	s_cselect_b64 s[56:57], -1, 0
	v_mov_b32_e32 v139, v155
	v_mov_b32_e32 v141, v155
	s_mov_b32 s92, 0
	v_add_u32_e32 v171, 0, v19
	s_mov_b32 s91, s8
	v_mov_b64_e32 v[2:3], 0
	v_mov_b64_e32 v[4:5], 0
	v_mov_b64_e32 v[6:7], 0
	v_mov_b64_e32 v[8:9], 0
	v_mov_b64_e32 v[10:11], 0
	v_mov_b64_e32 v[12:13], 0
	v_mov_b64_e32 v[14:15], 0
	v_mov_b64_e32 v[16:17], 0
	v_mov_b64_e32 v[18:19], 0
	v_mov_b64_e32 v[20:21], 0
	v_mov_b64_e32 v[22:23], 0
	v_mov_b64_e32 v[24:25], 0
	v_mov_b64_e32 v[26:27], 0
	v_mov_b64_e32 v[28:29], 0
	v_mov_b64_e32 v[30:31], 0
	v_mov_b64_e32 v[32:33], 0
	v_mov_b64_e32 v[34:35], 0
	v_mov_b64_e32 v[36:37], 0
	v_mov_b64_e32 v[38:39], 0
	v_mov_b64_e32 v[40:41], 0
	v_mov_b64_e32 v[42:43], 0
	v_mov_b64_e32 v[44:45], 0
	v_mov_b64_e32 v[46:47], 0
	v_mov_b64_e32 v[48:49], 0
	v_mov_b64_e32 v[50:51], 0
	v_mov_b64_e32 v[52:53], 0
	v_mov_b64_e32 v[54:55], 0
	v_mov_b64_e32 v[56:57], 0
	v_mov_b64_e32 v[58:59], 0
	v_mov_b64_e32 v[60:61], 0
	v_mov_b64_e32 v[62:63], 0
	v_mov_b64_e32 v[64:65], 0
	v_mov_b64_e32 v[66:67], 0
	v_mov_b64_e32 v[68:69], 0
	v_mov_b64_e32 v[70:71], 0
	v_mov_b64_e32 v[72:73], 0
	v_mov_b64_e32 v[74:75], 0
	v_mov_b64_e32 v[76:77], 0
	v_mov_b64_e32 v[78:79], 0
	v_mov_b64_e32 v[80:81], 0
	v_mov_b64_e32 v[82:83], 0
	v_mov_b64_e32 v[84:85], 0
	v_mov_b64_e32 v[86:87], 0
	v_mov_b64_e32 v[88:89], 0
	v_mov_b64_e32 v[90:91], 0
	v_mov_b64_e32 v[92:93], 0
	v_mov_b64_e32 v[94:95], 0
	v_mov_b64_e32 v[96:97], 0
	v_mov_b64_e32 v[98:99], 0
	v_mov_b64_e32 v[100:101], 0
	v_mov_b64_e32 v[102:103], 0
	v_mov_b64_e32 v[104:105], 0
	v_mov_b64_e32 v[106:107], 0
	v_mov_b64_e32 v[108:109], 0
	v_mov_b64_e32 v[110:111], 0
	v_mov_b64_e32 v[112:113], 0
	v_mov_b64_e32 v[114:115], 0
	v_mov_b64_e32 v[116:117], 0
	v_mov_b64_e32 v[118:119], 0
	v_mov_b64_e32 v[120:121], 0
	v_mov_b64_e32 v[122:123], 0
	v_mov_b64_e32 v[124:125], 0
	v_mov_b64_e32 v[126:127], 0
	v_mov_b64_e32 v[128:129], 0
	s_nop 0
	s_barrier
	v_readlane_b32 s9, v241, 21
	s_branch .LBB0_277
.LBB0_276:
	v_mov_b32_e32 v2, 0
	s_mov_b32 s87, s66
	s_mov_b32 s91, s62
	v_mov_b64_e32 v[2:3], 0
	v_mov_b64_e32 v[4:5], 0
	v_mov_b64_e32 v[6:7], 0
	v_mov_b64_e32 v[8:9], 0
	v_mov_b64_e32 v[10:11], 0
	v_mov_b64_e32 v[12:13], 0
	v_mov_b64_e32 v[14:15], 0
	v_mov_b64_e32 v[16:17], 0
	v_mov_b64_e32 v[18:19], 0
	v_mov_b64_e32 v[20:21], 0
	v_mov_b64_e32 v[22:23], 0
	v_mov_b64_e32 v[24:25], 0
	v_mov_b64_e32 v[26:27], 0
	v_mov_b64_e32 v[28:29], 0
	v_mov_b64_e32 v[30:31], 0
	v_mov_b64_e32 v[32:33], 0
	v_mov_b64_e32 v[34:35], 0
	v_mov_b64_e32 v[36:37], 0
	v_mov_b64_e32 v[38:39], 0
	v_mov_b64_e32 v[40:41], 0
	v_mov_b64_e32 v[42:43], 0
	v_mov_b64_e32 v[44:45], 0
	v_mov_b64_e32 v[46:47], 0
	v_mov_b64_e32 v[48:49], 0
	v_mov_b64_e32 v[50:51], 0
	v_mov_b64_e32 v[52:53], 0
	v_mov_b64_e32 v[54:55], 0
	v_mov_b64_e32 v[56:57], 0
	v_mov_b64_e32 v[58:59], 0
	v_mov_b64_e32 v[60:61], 0
	v_mov_b64_e32 v[62:63], 0
	v_mov_b64_e32 v[64:65], 0
	v_mov_b64_e32 v[66:67], 0
	v_mov_b64_e32 v[68:69], 0
	v_mov_b64_e32 v[70:71], 0
	v_mov_b64_e32 v[72:73], 0
	v_mov_b64_e32 v[74:75], 0
	v_mov_b64_e32 v[76:77], 0
	v_mov_b64_e32 v[78:79], 0
	v_mov_b64_e32 v[80:81], 0
	v_mov_b64_e32 v[82:83], 0
	v_mov_b64_e32 v[84:85], 0
	v_mov_b64_e32 v[86:87], 0
	v_mov_b64_e32 v[88:89], 0
	v_mov_b64_e32 v[90:91], 0
	v_mov_b64_e32 v[92:93], 0
	v_mov_b64_e32 v[94:95], 0
	v_mov_b64_e32 v[96:97], 0
	v_mov_b64_e32 v[98:99], 0
	v_mov_b64_e32 v[100:101], 0
	v_mov_b64_e32 v[102:103], 0
	v_mov_b64_e32 v[104:105], 0
	v_mov_b64_e32 v[106:107], 0
	v_mov_b64_e32 v[108:109], 0
	v_mov_b64_e32 v[110:111], 0
	v_mov_b64_e32 v[112:113], 0
	v_mov_b64_e32 v[114:115], 0
	v_mov_b64_e32 v[116:117], 0
	v_mov_b64_e32 v[118:119], 0
	v_mov_b64_e32 v[120:121], 0
	v_mov_b64_e32 v[122:123], 0
	v_mov_b64_e32 v[124:125], 0
	v_mov_b64_e32 v[126:127], 0
	v_mov_b64_e32 v[128:129], 0
	s_nop 0
	s_mov_b64 s[60:61], s[46:47]
	s_mov_b32 s92, s93
	s_andn2_b64 vcc, exec, s[36:37]
	s_mov_b64 s[10:11], s[8:9]
	s_cbranch_vccz .LBB0_329

.LBB0_464:
	s_add_u32 s12, s42, 0x10000
	s_addc_u32 s13, s43, 0
	v_bfe_u32 v18, v9, 4, 2
	s_lshl_b32 s39, s39, 5
	v_mov_b32_e32 v169, v155
	v_and_b32_e32 v13, 15, v9
	v_lshlrev_b32_e32 v19, 4, v18
	v_lshlrev_b32_e32 v9, 2, v9
	s_and_b32 s42, s39, 0x60
	s_add_i32 m0, s80, 0x18000
	v_lshl_add_u64 v[2:3], v[2:3], 0, s[34:35]
	v_lshl_add_u64 v[14:15], s[20:21], 0, v[168:169]
	v_mov_b32_e32 v167, v155
	v_lshl_or_b32 v196, s40, 6, v13
	v_lshl_or_b32 v13, v13, 6, v19
	s_lshl_b32 s40, s40, 13
	v_and_b32_e32 v9, 32, v9
	s_lshl_b32 s39, s42, 7
	s_waitcnt vmcnt(2)
	s_barrier
	global_load_lds_dwordx4 v[2:3], off
	v_lshl_add_u64 v[2:3], v[4:5], 0, s[34:35]
	s_add_i32 m0, s80, 0x1a000
	s_add_i32 s84, s80, 0x8000
	s_add_i32 s85, s80, 0xa000
	v_lshl_add_u64 v[16:17], s[20:21], 0, v[166:167]
	v_bitop3_b32 v19, v13, s40, v9 bitop3:0xde
	global_load_lds_dwordx4 v[2:3], off
	v_lshl_add_u64 v[2:3], v[14:15], 0, s[34:35]
	s_mov_b32 m0, s84
	s_add_u32 s40, s10, 0x80080
	global_load_lds_dwordx4 v[2:3], off
	v_lshl_add_u64 v[2:3], v[16:17], 0, s[34:35]
	s_mov_b32 m0, s85
	s_addc_u32 s41, s11, 0
	global_load_lds_dwordx4 v[2:3], off
	s_add_i32 m0, s80, 0x1c000
	v_lshl_add_u64 v[2:3], s[40:41], 0, v[154:155]
	global_load_lds_dwordx4 v[2:3], off
	v_lshl_add_u64 v[2:3], s[40:41], 0, v[164:165]
	s_add_i32 m0, s80, 0x1e000
	s_cmpk_lt_u32 s38, 0x100
	global_load_lds_dwordx4 v[2:3], off
	v_lshlrev_b32_e32 v2, 15, v11
	v_and_b32_e32 v2, 0xffff0000, v2
	v_lshl_add_u32 v2, v10, 12, v2
	v_and_b32_e32 v3, 1, v11
	v_lshl_or_b32 v2, v3, 6, v2
	v_lshl_add_u32 v170, v12, 1, v2
	v_lshlrev_b32_e32 v2, 15, v6
	v_and_b32_e32 v2, 0xffff0000, v2
	v_lshl_add_u32 v2, v7, 12, v2
	v_and_b32_e32 v3, 1, v6
	s_waitcnt vmcnt(6)
	v_lshl_or_b32 v2, v3, 6, v2
	v_lshl_add_u32 v172, v8, 1, v2
	v_mov_b32_e32 v2, 0
	v_readlane_b32 s40, v241, 22
	v_bitop3_b32 v197, v13, s39, v9 bitop3:0xde
	s_cselect_b64 s[46:47], -1, 0
	s_mov_b32 s91, 0
	v_cmp_eq_u32_e64 s[38:39], 0, v18
	v_lshl_or_b32 v199, v18, 3, s42
	v_mov_b32_e32 v171, v155
	v_mov_b32_e32 v173, v155
	v_add_u32_e32 v200, 0, v19
	v_readlane_b32 s86, v241, 17
	s_mov_b32 s87, s40
	s_mov_b64 s[56:57], s[20:21]
	v_mov_b64_e32 v[2:3], 0
	v_mov_b64_e32 v[4:5], 0
	v_mov_b64_e32 v[6:7], 0
	v_mov_b64_e32 v[8:9], 0
	v_mov_b64_e32 v[10:11], 0
	v_mov_b64_e32 v[12:13], 0
	v_mov_b64_e32 v[14:15], 0
	v_mov_b64_e32 v[16:17], 0
	v_mov_b64_e32 v[18:19], 0
	v_mov_b64_e32 v[20:21], 0
	v_mov_b64_e32 v[22:23], 0
	v_mov_b64_e32 v[24:25], 0
	v_mov_b64_e32 v[26:27], 0
	v_mov_b64_e32 v[28:29], 0
	v_mov_b64_e32 v[30:31], 0
	v_mov_b64_e32 v[32:33], 0
	v_mov_b64_e32 v[34:35], 0
	v_mov_b64_e32 v[36:37], 0
	v_mov_b64_e32 v[38:39], 0
	v_mov_b64_e32 v[40:41], 0
	v_mov_b64_e32 v[42:43], 0
	v_mov_b64_e32 v[44:45], 0
	v_mov_b64_e32 v[46:47], 0
	v_mov_b64_e32 v[48:49], 0
	v_mov_b64_e32 v[50:51], 0
	v_mov_b64_e32 v[52:53], 0
	v_mov_b64_e32 v[54:55], 0
	v_mov_b64_e32 v[56:57], 0
	v_mov_b64_e32 v[58:59], 0
	v_mov_b64_e32 v[60:61], 0
	v_mov_b64_e32 v[62:63], 0
	v_mov_b64_e32 v[64:65], 0
	v_mov_b64_e32 v[66:67], 0
	v_mov_b64_e32 v[68:69], 0
	v_mov_b64_e32 v[70:71], 0
	v_mov_b64_e32 v[72:73], 0
	v_mov_b64_e32 v[74:75], 0
	v_mov_b64_e32 v[76:77], 0
	v_mov_b64_e32 v[78:79], 0
	v_mov_b64_e32 v[80:81], 0
	v_mov_b64_e32 v[82:83], 0
	v_mov_b64_e32 v[84:85], 0
	v_mov_b64_e32 v[86:87], 0
	v_mov_b64_e32 v[88:89], 0
	v_mov_b64_e32 v[90:91], 0
	v_mov_b64_e32 v[92:93], 0
	v_mov_b64_e32 v[94:95], 0
	v_mov_b64_e32 v[96:97], 0
	v_mov_b64_e32 v[98:99], 0
	v_mov_b64_e32 v[100:101], 0
	v_mov_b64_e32 v[102:103], 0
	v_mov_b64_e32 v[104:105], 0
	v_mov_b64_e32 v[106:107], 0
	v_mov_b64_e32 v[108:109], 0
	v_mov_b64_e32 v[110:111], 0
	v_mov_b64_e32 v[112:113], 0
	v_mov_b64_e32 v[114:115], 0
	v_mov_b64_e32 v[116:117], 0
	v_mov_b64_e32 v[118:119], 0
	v_mov_b64_e32 v[120:121], 0
	v_mov_b64_e32 v[122:123], 0
	v_mov_b64_e32 v[124:125], 0
	v_mov_b64_e32 v[126:127], 0
	v_mov_b64_e32 v[128:129], 0
	s_nop 0
	s_barrier
	v_readlane_b32 s41, v241, 23
	s_branch .LBB0_466
.LBB0_465:
	v_mov_b32_e32 v2, 0
	s_mov_b32 s86, s52
	s_mov_b32 s87, s54
	v_mov_b64_e32 v[2:3], 0
	v_mov_b64_e32 v[4:5], 0
	v_mov_b64_e32 v[6:7], 0
	v_mov_b64_e32 v[8:9], 0
	v_mov_b64_e32 v[10:11], 0
	v_mov_b64_e32 v[12:13], 0
	v_mov_b64_e32 v[14:15], 0
	v_mov_b64_e32 v[16:17], 0
	v_mov_b64_e32 v[18:19], 0
	v_mov_b64_e32 v[20:21], 0
	v_mov_b64_e32 v[22:23], 0
	v_mov_b64_e32 v[24:25], 0
	v_mov_b64_e32 v[26:27], 0
	v_mov_b64_e32 v[28:29], 0
	v_mov_b64_e32 v[30:31], 0
	v_mov_b64_e32 v[32:33], 0
	v_mov_b64_e32 v[34:35], 0
	v_mov_b64_e32 v[36:37], 0
	v_mov_b64_e32 v[38:39], 0
	v_mov_b64_e32 v[40:41], 0
	v_mov_b64_e32 v[42:43], 0
	v_mov_b64_e32 v[44:45], 0
	v_mov_b64_e32 v[46:47], 0
	v_mov_b64_e32 v[48:49], 0
	v_mov_b64_e32 v[50:51], 0
	v_mov_b64_e32 v[52:53], 0
	v_mov_b64_e32 v[54:55], 0
	v_mov_b64_e32 v[56:57], 0
	v_mov_b64_e32 v[58:59], 0
	v_mov_b64_e32 v[60:61], 0
	v_mov_b64_e32 v[62:63], 0
	v_mov_b64_e32 v[64:65], 0
	v_mov_b64_e32 v[66:67], 0
	v_mov_b64_e32 v[68:69], 0
	v_mov_b64_e32 v[70:71], 0
	v_mov_b64_e32 v[72:73], 0
	v_mov_b64_e32 v[74:75], 0
	v_mov_b64_e32 v[76:77], 0
	v_mov_b64_e32 v[78:79], 0
	v_mov_b64_e32 v[80:81], 0
	v_mov_b64_e32 v[82:83], 0
	v_mov_b64_e32 v[84:85], 0
	v_mov_b64_e32 v[86:87], 0
	v_mov_b64_e32 v[88:89], 0
	v_mov_b64_e32 v[90:91], 0
	v_mov_b64_e32 v[92:93], 0
	v_mov_b64_e32 v[94:95], 0
	v_mov_b64_e32 v[96:97], 0
	v_mov_b64_e32 v[98:99], 0
	v_mov_b64_e32 v[100:101], 0
	v_mov_b64_e32 v[102:103], 0
	v_mov_b64_e32 v[104:105], 0
	v_mov_b64_e32 v[106:107], 0
	v_mov_b64_e32 v[108:109], 0
	v_mov_b64_e32 v[110:111], 0
	v_mov_b64_e32 v[112:113], 0
	v_mov_b64_e32 v[114:115], 0
	v_mov_b64_e32 v[116:117], 0
	v_mov_b64_e32 v[118:119], 0
	v_mov_b64_e32 v[120:121], 0
	v_mov_b64_e32 v[122:123], 0
	v_mov_b64_e32 v[124:125], 0
	v_mov_b64_e32 v[126:127], 0
	v_mov_b64_e32 v[128:129], 0
	s_nop 0
	s_mov_b64 s[56:57], s[62:63]
	s_mov_b32 s91, s92
	s_andn2_b64 vcc, exec, s[40:41]
	s_mov_b64 s[10:11], s[60:61]
	s_cbranch_vccz .LBB0_496

.LBB0_595:
	v_readlane_b32 s10, v242, 13
	s_add_u32 s48, s10, 0x20000
	v_readlane_b32 s10, v240, 10
	s_waitcnt vmcnt(0)
	v_lshrrev_b32_e32 v19, 1, v2
	s_addc_u32 s49, s10, 0
	v_and_b32_e32 v19, 24, v19
	s_and_b64 s[10:11], s[34:35], exec
	v_and_b32_e32 v18, 15, v2
	v_lshlrev_b32_e32 v20, 1, v19
	v_lshlrev_b32_e32 v2, 2, v2
	s_cselect_b32 s37, 16, 0
	s_and_b32 s10, s8, 3
	v_lshl_or_b32 v177, s9, 6, v18
	v_lshl_or_b32 v18, v18, 6, v20
	s_lshl_b32 s9, s9, 13
	v_and_b32_e32 v2, 32, v2
	s_add_i32 m0, s25, 0x18000
	v_lshl_add_u64 v[10:11], v[10:11], 0, s[28:29]
	v_bitop3_b32 v20, v18, s9, v2 bitop3:0xde
	s_lshl_b32 s9, s10, 5
	s_lshl_b32 s10, s10, 12
	s_waitcnt vmcnt(2)
	s_barrier
	global_load_lds_dwordx4 v[10:11], off
	v_lshl_add_u64 v[8:9], v[8:9], 0, s[28:29]
	s_add_i32 m0, s25, 0x1a000
	s_add_i32 s45, s25, 0x8000
	s_add_i32 s60, s25, 0xa000
	v_bitop3_b32 v204, v18, s10, v2 bitop3:0xde
	global_load_lds_dwordx4 v[8:9], off
	v_lshl_add_u64 v[4:5], v[4:5], 0, s[28:29]
	s_mov_b32 m0, s45
	s_add_u32 s10, s0, 0x80080
	global_load_lds_dwordx4 v[4:5], off
	v_lshl_add_u64 v[4:5], v[6:7], 0, s[28:29]
	s_mov_b32 m0, s60
	s_addc_u32 s11, s1, 0
	global_load_lds_dwordx4 v[4:5], off
	s_add_i32 m0, s25, 0x1c000
	v_lshl_add_u64 v[4:5], s[10:11], 0, v[170:171]
	global_load_lds_dwordx4 v[4:5], off
	v_lshl_add_u64 v[4:5], s[10:11], 0, v[174:175]
	s_add_i32 m0, s25, 0x1e000
	s_cmpk_lt_u32 s13, 0x100
	global_load_lds_dwordx4 v[4:5], off
	s_cselect_b64 s[50:51], -1, 0
	s_lshl_b32 s61, s12, 3
	v_cvt_f32_u32_e32 v2, s61
	v_or_b32_e32 v176, s9, v19
	v_bitop3_b32 v6, s9, 56, v19 bitop3:0xc8
	s_bfe_u32 s62, s8, 0x10001
	v_rcp_iflag_f32_e32 v4, v2
	v_readlane_b32 s8, v241, 38
	v_lshlrev_b32_e32 v2, 2, v6
	v_readlane_b32 s9, v241, 39
	v_mul_f32_e32 v4, 0x4f7ffffe, v4
	v_cvt_u32_f32_e32 v4, v4
	v_lshl_add_u64 v[178:179], s[8:9], 0, v[2:3]
	v_readlane_b32 s8, v241, 40
	v_readlane_b32 s9, v241, 41
	s_waitcnt vmcnt(6)
	s_mov_b32 s74, 0
	s_lshl_b32 s63, s12, 2
	v_lshl_add_u64 v[180:181], s[8:9], 0, v[2:3]
	v_lshlrev_b32_e32 v2, 15, v12
	v_and_b32_e32 v2, 0xffff0000, v2
	v_readfirstlane_b32 s9, v4
	v_lshl_add_u32 v2, v13, 12, v2
	v_and_b32_e32 v4, 1, v12
	v_lshl_or_b32 v2, v4, 6, v2
	v_lshl_add_u32 v182, v14, 1, v2
	v_lshlrev_b32_e32 v2, 15, v15
	s_sub_i32 s8, 0, s61
	v_and_b32_e32 v2, 0xffff0000, v2
	s_mul_i32 s8, s8, s9
	v_lshl_add_u32 v2, v16, 12, v2
	v_and_b32_e32 v4, 1, v15
	s_mul_hi_u32 s8, s9, s8
	v_lshl_or_b32 v2, v4, 6, v2
	v_mov_b32_e32 v4, 0
	s_add_i32 s67, s9, s8
	v_mov_b32_e32 v183, v3
	v_lshl_add_u32 v184, v17, 1, v2
	v_mov_b32_e32 v185, v3
	v_add_u32_e32 v205, 0, v20
	v_lshlrev_b32_e32 v2, 1, v6
	v_mov_b64_e32 v[4:5], 0
	v_mov_b64_e32 v[6:7], 0
	v_mov_b64_e32 v[8:9], 0
	v_mov_b64_e32 v[10:11], 0
	v_mov_b64_e32 v[12:13], 0
	v_mov_b64_e32 v[14:15], 0
	v_mov_b64_e32 v[16:17], 0
	v_mov_b64_e32 v[18:19], 0
	v_mov_b64_e32 v[20:21], 0
	v_mov_b64_e32 v[22:23], 0
	v_mov_b64_e32 v[24:25], 0
	v_mov_b64_e32 v[26:27], 0
	v_mov_b64_e32 v[28:29], 0
	v_mov_b64_e32 v[30:31], 0
	v_mov_b64_e32 v[32:33], 0
	v_mov_b64_e32 v[34:35], 0
	v_mov_b64_e32 v[36:37], 0
	v_mov_b64_e32 v[38:39], 0
	v_mov_b64_e32 v[40:41], 0
	v_mov_b64_e32 v[42:43], 0
	v_mov_b64_e32 v[44:45], 0
	v_mov_b64_e32 v[46:47], 0
	v_mov_b64_e32 v[48:49], 0
	v_mov_b64_e32 v[50:51], 0
	v_mov_b64_e32 v[52:53], 0
	v_mov_b64_e32 v[54:55], 0
	v_mov_b64_e32 v[56:57], 0
	v_mov_b64_e32 v[58:59], 0
	v_mov_b64_e32 v[60:61], 0
	v_mov_b64_e32 v[62:63], 0
	v_mov_b64_e32 v[64:65], 0
	v_mov_b64_e32 v[66:67], 0
	v_mov_b64_e32 v[68:69], 0
	v_mov_b64_e32 v[70:71], 0
	v_mov_b64_e32 v[72:73], 0
	v_mov_b64_e32 v[74:75], 0
	v_mov_b64_e32 v[76:77], 0
	v_mov_b64_e32 v[78:79], 0
	v_mov_b64_e32 v[80:81], 0
	v_mov_b64_e32 v[82:83], 0
	v_mov_b64_e32 v[84:85], 0
	v_mov_b64_e32 v[86:87], 0
	v_mov_b64_e32 v[88:89], 0
	v_mov_b64_e32 v[90:91], 0
	v_mov_b64_e32 v[92:93], 0
	v_mov_b64_e32 v[94:95], 0
	v_mov_b64_e32 v[96:97], 0
	v_mov_b64_e32 v[98:99], 0
	v_mov_b64_e32 v[100:101], 0
	v_mov_b64_e32 v[102:103], 0
	v_mov_b64_e32 v[104:105], 0
	v_mov_b64_e32 v[106:107], 0
	v_mov_b64_e32 v[108:109], 0
	v_mov_b64_e32 v[110:111], 0
	v_mov_b64_e32 v[112:113], 0
	v_mov_b64_e32 v[114:115], 0
	v_mov_b64_e32 v[116:117], 0
	v_mov_b64_e32 v[118:119], 0
	v_mov_b64_e32 v[120:121], 0
	v_mov_b64_e32 v[122:123], 0
	v_mov_b64_e32 v[124:125], 0
	v_mov_b64_e32 v[126:127], 0
	v_mov_b64_e32 v[128:129], 0
	v_mov_b64_e32 v[130:131], 0
	s_nop 0
	s_barrier
	s_branch .LBB0_597
.LBB0_596:
	v_mov_b32_e32 v4, 0
	s_mov_b32 s66, s42
	s_mov_b32 s44, s54
	v_mov_b64_e32 v[4:5], 0
	v_mov_b64_e32 v[6:7], 0
	v_mov_b64_e32 v[8:9], 0
	v_mov_b64_e32 v[10:11], 0
	v_mov_b64_e32 v[12:13], 0
	v_mov_b64_e32 v[14:15], 0
	v_mov_b64_e32 v[16:17], 0
	v_mov_b64_e32 v[18:19], 0
	v_mov_b64_e32 v[20:21], 0
	v_mov_b64_e32 v[22:23], 0
	v_mov_b64_e32 v[24:25], 0
	v_mov_b64_e32 v[26:27], 0
	v_mov_b64_e32 v[28:29], 0
	v_mov_b64_e32 v[30:31], 0
	v_mov_b64_e32 v[32:33], 0
	v_mov_b64_e32 v[34:35], 0
	v_mov_b64_e32 v[36:37], 0
	v_mov_b64_e32 v[38:39], 0
	v_mov_b64_e32 v[40:41], 0
	v_mov_b64_e32 v[42:43], 0
	v_mov_b64_e32 v[44:45], 0
	v_mov_b64_e32 v[46:47], 0
	v_mov_b64_e32 v[48:49], 0
	v_mov_b64_e32 v[50:51], 0
	v_mov_b64_e32 v[52:53], 0
	v_mov_b64_e32 v[54:55], 0
	v_mov_b64_e32 v[56:57], 0
	v_mov_b64_e32 v[58:59], 0
	v_mov_b64_e32 v[60:61], 0
	v_mov_b64_e32 v[62:63], 0
	v_mov_b64_e32 v[64:65], 0
	v_mov_b64_e32 v[66:67], 0
	v_mov_b64_e32 v[68:69], 0
	v_mov_b64_e32 v[70:71], 0
	v_mov_b64_e32 v[72:73], 0
	v_mov_b64_e32 v[74:75], 0
	v_mov_b64_e32 v[76:77], 0
	v_mov_b64_e32 v[78:79], 0
	v_mov_b64_e32 v[80:81], 0
	v_mov_b64_e32 v[82:83], 0
	v_mov_b64_e32 v[84:85], 0
	v_mov_b64_e32 v[86:87], 0
	v_mov_b64_e32 v[88:89], 0
	v_mov_b64_e32 v[90:91], 0
	v_mov_b64_e32 v[92:93], 0
	v_mov_b64_e32 v[94:95], 0
	v_mov_b64_e32 v[96:97], 0
	v_mov_b64_e32 v[98:99], 0
	v_mov_b64_e32 v[100:101], 0
	v_mov_b64_e32 v[102:103], 0
	v_mov_b64_e32 v[104:105], 0
	v_mov_b64_e32 v[106:107], 0
	v_mov_b64_e32 v[108:109], 0
	v_mov_b64_e32 v[110:111], 0
	v_mov_b64_e32 v[112:113], 0
	v_mov_b64_e32 v[114:115], 0
	v_mov_b64_e32 v[116:117], 0
	v_mov_b64_e32 v[118:119], 0
	v_mov_b64_e32 v[120:121], 0
	v_mov_b64_e32 v[122:123], 0
	v_mov_b64_e32 v[124:125], 0
	v_mov_b64_e32 v[126:127], 0
	v_mov_b64_e32 v[128:129], 0
	v_mov_b64_e32 v[130:131], 0
	s_nop 0
	s_mov_b64 s[52:53], s[56:57]
	s_mov_b32 s74, s75
	s_andn2_b64 vcc, exec, s[38:39]
	s_mov_b64 s[0:1], s[34:35]
	s_cbranch_vccz .LBB0_650

.LBB0_857:
	v_readlane_b32 s8, v242, 13
	s_add_u32 s8, s8, 0x30000
	v_readlane_b32 s9, v240, 10
	v_readlane_b32 s34, v240, 2
	s_addc_u32 s9, s9, 0
	s_waitcnt vmcnt(0)
	v_bfe_u32 v20, v11, 4, 2
	s_lshl_b32 s13, s13, 5
	v_mov_b32_e32 v161, v3
	v_readlane_b32 s35, v240, 3
	v_and_b32_e32 v15, 15, v11
	v_lshlrev_b32_e32 v21, 4, v20
	v_lshlrev_b32_e32 v11, 2, v11
	s_and_b32 s24, s13, 0x60
	s_add_i32 m0, s48, 0x18000
	v_lshl_add_u64 v[4:5], v[4:5], 0, s[28:29]
	v_lshl_add_u64 v[16:17], s[34:35], 0, v[160:161]
	v_mov_b32_e32 v159, v3
	v_lshl_or_b32 v188, s14, 6, v15
	v_lshl_or_b32 v15, v15, 6, v21
	s_lshl_b32 s14, s14, 13
	v_and_b32_e32 v11, 32, v11
	s_lshl_b32 s13, s24, 7
	s_waitcnt vmcnt(2)
	s_barrier
	global_load_lds_dwordx4 v[4:5], off
	v_lshl_add_u64 v[4:5], v[6:7], 0, s[28:29]
	s_add_i32 m0, s48, 0x1a000
	s_add_i32 s52, s48, 0x8000
	s_add_i32 s53, s48, 0xa000
	v_lshl_add_u64 v[18:19], s[34:35], 0, v[158:159]
	v_bitop3_b32 v21, v15, s14, v11 bitop3:0xde
	global_load_lds_dwordx4 v[4:5], off
	v_lshl_add_u64 v[4:5], v[16:17], 0, s[28:29]
	s_mov_b32 m0, s52
	s_add_u32 s14, s10, 0x80080
	global_load_lds_dwordx4 v[4:5], off
	v_lshl_add_u64 v[4:5], v[18:19], 0, s[28:29]
	s_mov_b32 m0, s53
	s_addc_u32 s15, s11, 0
	global_load_lds_dwordx4 v[4:5], off
	s_add_i32 m0, s48, 0x1c000
	v_lshl_add_u64 v[4:5], s[14:15], 0, v[2:3]
	global_load_lds_dwordx4 v[4:5], off
	v_lshl_add_u64 v[4:5], s[14:15], 0, v[156:157]
	s_add_i32 m0, s48, 0x1e000
	s_cmpk_lt_u32 s12, 0x100
	global_load_lds_dwordx4 v[4:5], off
	v_lshlrev_b32_e32 v4, 15, v13
	v_and_b32_e32 v4, 0xffff0000, v4
	v_lshl_add_u32 v4, v12, 12, v4
	v_and_b32_e32 v5, 1, v13
	v_lshl_or_b32 v4, v5, 6, v4
	v_lshl_add_u32 v162, v14, 1, v4
	v_lshlrev_b32_e32 v4, 15, v8
	v_and_b32_e32 v4, 0xffff0000, v4
	v_lshl_add_u32 v4, v9, 12, v4
	v_and_b32_e32 v5, 1, v8
	s_waitcnt vmcnt(6)
	v_lshl_or_b32 v4, v5, 6, v4
	v_lshl_add_u32 v168, v10, 1, v4
	v_mov_b32_e32 v4, 0
	v_readlane_b32 s14, v241, 22
	v_bitop3_b32 v189, v15, s13, v11 bitop3:0xde
	s_cselect_b64 s[12:13], -1, 0
	s_mov_b32 s56, 0
	v_cmp_eq_u32_e64 s[38:39], 0, v20
	v_lshl_or_b32 v190, v20, 3, s24
	v_mov_b32_e32 v163, v3
	v_mov_b32_e32 v169, v3
	v_add_u32_e32 v191, 0, v21
	v_readlane_b32 s54, v241, 17
	s_mov_b32 s55, s14
	v_mov_b64_e32 v[4:5], 0
	v_mov_b64_e32 v[6:7], 0
	v_mov_b64_e32 v[8:9], 0
	v_mov_b64_e32 v[10:11], 0
	v_mov_b64_e32 v[12:13], 0
	v_mov_b64_e32 v[14:15], 0
	v_mov_b64_e32 v[16:17], 0
	v_mov_b64_e32 v[18:19], 0
	v_mov_b64_e32 v[20:21], 0
	v_mov_b64_e32 v[22:23], 0
	v_mov_b64_e32 v[24:25], 0
	v_mov_b64_e32 v[26:27], 0
	v_mov_b64_e32 v[28:29], 0
	v_mov_b64_e32 v[30:31], 0
	v_mov_b64_e32 v[32:33], 0
	v_mov_b64_e32 v[34:35], 0
	v_mov_b64_e32 v[36:37], 0
	v_mov_b64_e32 v[38:39], 0
	v_mov_b64_e32 v[40:41], 0
	v_mov_b64_e32 v[42:43], 0
	v_mov_b64_e32 v[44:45], 0
	v_mov_b64_e32 v[46:47], 0
	v_mov_b64_e32 v[48:49], 0
	v_mov_b64_e32 v[50:51], 0
	v_mov_b64_e32 v[52:53], 0
	v_mov_b64_e32 v[54:55], 0
	v_mov_b64_e32 v[56:57], 0
	v_mov_b64_e32 v[58:59], 0
	v_mov_b64_e32 v[60:61], 0
	v_mov_b64_e32 v[62:63], 0
	v_mov_b64_e32 v[64:65], 0
	v_mov_b64_e32 v[66:67], 0
	v_mov_b64_e32 v[68:69], 0
	v_mov_b64_e32 v[70:71], 0
	v_mov_b64_e32 v[72:73], 0
	v_mov_b64_e32 v[74:75], 0
	v_mov_b64_e32 v[76:77], 0
	v_mov_b64_e32 v[78:79], 0
	v_mov_b64_e32 v[80:81], 0
	v_mov_b64_e32 v[82:83], 0
	v_mov_b64_e32 v[84:85], 0
	v_mov_b64_e32 v[86:87], 0
	v_mov_b64_e32 v[88:89], 0
	v_mov_b64_e32 v[90:91], 0
	v_mov_b64_e32 v[92:93], 0
	v_mov_b64_e32 v[94:95], 0
	v_mov_b64_e32 v[96:97], 0
	v_mov_b64_e32 v[98:99], 0
	v_mov_b64_e32 v[100:101], 0
	v_mov_b64_e32 v[102:103], 0
	v_mov_b64_e32 v[104:105], 0
	v_mov_b64_e32 v[106:107], 0
	v_mov_b64_e32 v[108:109], 0
	v_mov_b64_e32 v[110:111], 0
	v_mov_b64_e32 v[112:113], 0
	v_mov_b64_e32 v[114:115], 0
	v_mov_b64_e32 v[116:117], 0
	v_mov_b64_e32 v[118:119], 0
	v_mov_b64_e32 v[120:121], 0
	v_mov_b64_e32 v[122:123], 0
	v_mov_b64_e32 v[124:125], 0
	v_mov_b64_e32 v[126:127], 0
	v_mov_b64_e32 v[128:129], 0
	v_mov_b64_e32 v[130:131], 0
	s_nop 0
	s_barrier
	v_readlane_b32 s15, v241, 23
	s_branch .LBB0_859
.LBB0_858:
	v_mov_b32_e32 v4, 0
	s_mov_b32 s54, s14
	s_mov_b32 s55, s26
	v_mov_b64_e32 v[4:5], 0
	v_mov_b64_e32 v[6:7], 0
	v_mov_b64_e32 v[8:9], 0
	v_mov_b64_e32 v[10:11], 0
	v_mov_b64_e32 v[12:13], 0
	v_mov_b64_e32 v[14:15], 0
	v_mov_b64_e32 v[16:17], 0
	v_mov_b64_e32 v[18:19], 0
	v_mov_b64_e32 v[20:21], 0
	v_mov_b64_e32 v[22:23], 0
	v_mov_b64_e32 v[24:25], 0
	v_mov_b64_e32 v[26:27], 0
	v_mov_b64_e32 v[28:29], 0
	v_mov_b64_e32 v[30:31], 0
	v_mov_b64_e32 v[32:33], 0
	v_mov_b64_e32 v[34:35], 0
	v_mov_b64_e32 v[36:37], 0
	v_mov_b64_e32 v[38:39], 0
	v_mov_b64_e32 v[40:41], 0
	v_mov_b64_e32 v[42:43], 0
	v_mov_b64_e32 v[44:45], 0
	v_mov_b64_e32 v[46:47], 0
	v_mov_b64_e32 v[48:49], 0
	v_mov_b64_e32 v[50:51], 0
	v_mov_b64_e32 v[52:53], 0
	v_mov_b64_e32 v[54:55], 0
	v_mov_b64_e32 v[56:57], 0
	v_mov_b64_e32 v[58:59], 0
	v_mov_b64_e32 v[60:61], 0
	v_mov_b64_e32 v[62:63], 0
	v_mov_b64_e32 v[64:65], 0
	v_mov_b64_e32 v[66:67], 0
	v_mov_b64_e32 v[68:69], 0
	v_mov_b64_e32 v[70:71], 0
	v_mov_b64_e32 v[72:73], 0
	v_mov_b64_e32 v[74:75], 0
	v_mov_b64_e32 v[76:77], 0
	v_mov_b64_e32 v[78:79], 0
	v_mov_b64_e32 v[80:81], 0
	v_mov_b64_e32 v[82:83], 0
	v_mov_b64_e32 v[84:85], 0
	v_mov_b64_e32 v[86:87], 0
	v_mov_b64_e32 v[88:89], 0
	v_mov_b64_e32 v[90:91], 0
	v_mov_b64_e32 v[92:93], 0
	v_mov_b64_e32 v[94:95], 0
	v_mov_b64_e32 v[96:97], 0
	v_mov_b64_e32 v[98:99], 0
	v_mov_b64_e32 v[100:101], 0
	v_mov_b64_e32 v[102:103], 0
	v_mov_b64_e32 v[104:105], 0
	v_mov_b64_e32 v[106:107], 0
	v_mov_b64_e32 v[108:109], 0
	v_mov_b64_e32 v[110:111], 0
	v_mov_b64_e32 v[112:113], 0
	v_mov_b64_e32 v[114:115], 0
	v_mov_b64_e32 v[116:117], 0
	v_mov_b64_e32 v[118:119], 0
	v_mov_b64_e32 v[120:121], 0
	v_mov_b64_e32 v[122:123], 0
	v_mov_b64_e32 v[124:125], 0
	v_mov_b64_e32 v[126:127], 0
	v_mov_b64_e32 v[128:129], 0
	v_mov_b64_e32 v[130:131], 0
	s_nop 0
	s_mov_b64 s[34:35], s[44:45]
	s_mov_b32 s56, s57
	s_andn2_b64 vcc, exec, s[40:41]
	s_mov_b64 s[10:11], s[36:37]
	s_cbranch_vccz .LBB0_889
